# counted waits in rw_mix: the nine parameter-vector loads are issued together with the four row loads (one memory round trip per row instead of two); waits re-derived
# speedup vs baseline: 1.0022x; 1.0022x over previous
; #define LAS __attribute__((address_space(3)))
; DI const float* modp(const unsigned char* ws, int layer, int who, int idx) { return (const float*)(ws + WS_MOD) + ((size_t)(layer * 9 + who) * 6 + idx) * D; }
; DI void phase_rw_mix(int layer, int j, int q, LAS unsigned char* lds) {
;     ...
;         for (int rr = wave; rr < 19; rr += 8) {
;             const int t = t0 - 1 + rr;
;             if (t < 0 || t >= T) {
; #pragma unroll
;                 for (int jj = 0; jj < 4; ++jj) *(LAS f32x4*)(hs + rr * 1024 + 4 * lane + 256 * jj) = (f32x4){0.f, 0.f, 0.f, 0.f};
;             } else {
;                 const int who = t < LC ? 8 : b; const float* sh = modp(ws, layer, who, 0); const float* sc = modp(ws, layer, who, 1);
;                 const float* z = zrow(ws, outp, b * T + t); f32x4 v[4]; float ss = 0.f;
; #pragma unroll
;                 for (int jj = 0; jj < 4; ++jj) { v[jj] = *(const f32x4*)(z + 4 * lane + 256 * jj); ss += v[jj][0] * v[jj][0] + v[jj][1] * v[jj][1] + v[jj][2] * v[jj][2] + v[jj][3] * v[jj][3]; }
;                 const float rstd = rsqrtf(wave_sum(ss) * (1.f / D) + 1e-6f);
; #pragma unroll
;                 for (int jj = 0; jj < 4; ++jj) { const int c = 4 * lane + 256 * jj;
;                     const f32x4 gg = *(const f32x4*)(g + c), a1 = *(const f32x4*)(sc + c), a0 = *(const f32x4*)(sh + c);
.LBB0_455:
	v_add3_u32 v5, s22, v21, 7
	s_movk_i32 s2, 0x1100
	v_cmp_gt_u32_e32 vcc, s2, v5
	s_and_saveexec_b64 s[2:3], vcc
	s_xor_b64 s[18:19], exec, s[2:3]
	s_cbranch_execz .LBB0_461
	v_add_u32_e32 v8, s23, v21
	v_add_u32_e32 v2, 7, v8
	s_mov_b32 s2, 0x78787879
	v_mul_hi_i32 v3, v2, s2
	v_lshrrev_b32_e32 v4, 31, v3
	v_ashrrev_i32_e32 v3, 11, v3
	v_add_u32_e32 v6, v3, v4
	s_movk_i32 s2, 0xef00
	v_mad_i32_i24 v2, v6, s2, v2
	s_movk_i32 s2, 0xff
	v_mul_i32_i24_e32 v7, 0xffffef00, v6
	v_cmp_lt_i32_e32 vcc, s2, v2
	v_mov_b64_e32 v[2:3], s[6:7]
	s_and_saveexec_b64 s[2:3], vcc
	s_xor_b64 s[2:3], exec, s[2:3]
	v_lshl_add_u32 v2, v6, 12, v7
	s_movk_i32 s28, 0xff07
	v_add3_u32 v4, v8, v2, s28
	v_mov_b64_e32 v[2:3], s[10:11]
	s_andn2_saveexec_b64 s[2:3], s[2:3]
	v_add_u32_e32 v4, s25, v25
	v_lshlrev_b32_e32 v6, 8, v6
	v_add3_u32 v4, v7, v4, v6
	s_or_b64 exec, exec, s[2:3]
	s_movk_i32 s2, 0xff
	v_cmp_lt_u32_e32 vcc, s2, v5
	v_mov_b32_e32 v5, s24
	v_readlane_b32 s2, v255, 31
	v_cndmask_b32_e32 v5, 8, v5, vcc
	s_mul_i32 s2, s2, 9
	v_add_u32_e32 v5, s2, v5
	v_mul_i32_i24_e32 v6, 6, v5
	v_ashrrev_i32_e32 v5, 31, v4
	v_lshlrev_b64 v[4:5], 12, v[4:5]
	v_lshl_add_u64 v[2:3], v[2:3], 0, v[4:5]
	v_lshl_add_u64 v[2:3], v[2:3], 0, v[0:1]
	global_load_dwordx4 v[26:29], v[2:3], off
	global_load_dwordx4 v[10:13], v[2:3], off offset:1024
	global_load_dwordx4 v[108:111], v[2:3], off offset:2048
	global_load_dwordx4 v[112:115], v[2:3], off offset:3072
	v_ashrrev_i32_e32 v7, 31, v6
	v_lshlrev_b64 v[6:7], 12, v[6:7]
	v_lshl_add_u64 v[14:15], s[12:13], 0, v[6:7]
	v_xor_b32_e32 v20, 1, v187
	s_mov_b64 s[2:3], 0x1000
	v_lshl_add_u64 v[18:19], v[14:15], 0, s[2:3]
	s_mov_b32 s2, 0x800000
	v_mov_b32_e32 v79, v1
	v_mov_b32_e32 v81, v1
	v_mov_b32_e32 v83, v1
	v_lshl_add_u64 v[162:163], v[14:15], 0, v[0:1]
	global_load_dwordx4 v[116:119], v[52:53], off offset:1024
	v_lshl_add_u64 v[152:153], v[18:19], 0, v[78:79]
	global_load_dwordx4 v[120:123], v[152:153], off
	global_load_dwordx4 v[124:127], v[162:163], off offset:1024
	global_load_dwordx4 v[128:131], v[52:53], off offset:2048
	v_lshl_add_u64 v[154:155], v[18:19], 0, v[80:81]
	global_load_dwordx4 v[132:135], v[154:155], off
	global_load_dwordx4 v[140:143], v[162:163], off offset:2048
	global_load_dwordx4 v[144:147], v[52:53], off offset:3072
	v_lshl_add_u64 v[156:157], v[18:19], 0, v[82:83]
	global_load_dwordx4 v[148:151], v[156:157], off
	global_load_dwordx4 v[158:161], v[162:163], off offset:3072
	s_waitcnt vmcnt(12)
	v_mov_b32_e32 v6, v27
	s_waitcnt vmcnt(11)
	v_mov_b32_e32 v7, v11
	v_mov_b32_e32 v4, v26
	v_mov_b32_e32 v5, v10
	v_pk_mul_f32 v[6:7], v[6:7], v[6:7]
	s_nop 0
	v_pk_fma_f32 v[4:5], v[4:5], v[4:5], v[6:7]
	v_mov_b32_e32 v6, v28
	v_mov_b32_e32 v7, v12
	v_pk_fma_f32 v[4:5], v[6:7], v[6:7], v[4:5]
	v_mov_b32_e32 v6, v29
	v_mov_b32_e32 v7, v13
	v_pk_fma_f32 v[16:17], v[6:7], v[6:7], v[4:5]
	s_waitcnt vmcnt(9)
	v_mov_b64_e32 v[6:7], v[108:109]
	v_mov_b64_e32 v[8:9], v[110:111]
	v_mov_b64_e32 v[4:5], v[114:115]
	v_mov_b64_e32 v[2:3], v[112:113]
	v_add_f32_e32 v16, v16, v17
	v_and_b32_e32 v17, 64, v187
	v_add_u32_e32 v17, 64, v17
	v_cmp_lt_i32_e32 vcc, v20, v17
	s_waitcnt vmcnt(9)
	v_mov_b32_e32 v30, v7
	s_waitcnt vmcnt(9)
; #define LAS __attribute__((address_space(3)))
; DI void phase_rw_mix(int layer, int j, int q, LAS unsigned char* lds) {
;     ...
; #pragma unroll
;                 for (int jj = 0; jj < 4; ++jj) { v[jj] = *(const f32x4*)(z + 4 * lane + 256 * jj); ss += v[jj][0] * v[jj][0] + v[jj][1] * v[jj][1] + v[jj][2] * v[jj][2] + v[jj][3] * v[jj][3]; }
;                 const float rstd = rsqrtf(wave_sum(ss) * (1.f / D) + 1e-6f);
; #pragma unroll
;                 for (int jj = 0; jj < 4; ++jj) { const int c = 4 * lane + 256 * jj;
;                     const f32x4 gg = *(const f32x4*)(g + c), a1 = *(const f32x4*)(sc + c), a0 = *(const f32x4*)(sh + c);
;                     f32x4 y = v[jj] * rstd * gg; y = y * (a1 + 1.f) + a0; *(LAS f32x4*)(hs + rr * 1024 + c) = y; }
;             }
	v_mov_b32_e32 v31, v3
	v_mov_b32_e32 v22, v6
	v_mov_b32_e32 v23, v2
	v_pk_mul_f32 v[30:31], v[30:31], v[30:31]
	v_cndmask_b32_e32 v20, v187, v20, vcc
	v_pk_fma_f32 v[22:23], v[22:23], v[22:23], v[30:31]
	v_mov_b32_e32 v30, v8
	v_mov_b32_e32 v31, v4
	v_pk_fma_f32 v[22:23], v[30:31], v[30:31], v[22:23]
	v_mov_b32_e32 v30, v9
	v_mov_b32_e32 v31, v5
	v_pk_fma_f32 v[22:23], v[30:31], v[30:31], v[22:23]
	v_lshlrev_b32_e32 v20, 2, v20
	v_add_f32_e32 v16, v16, v22
	v_add_f32_e32 v16, v16, v23
	v_mov_b32_e32 v166, v16
	s_nop 1
	v_add_f32_dpp v166, v166, v166 row_shr:1 row_mask:0xf bank_mask:0xf
	s_nop 1
	v_add_f32_dpp v166, v166, v166 row_shr:2 row_mask:0xf bank_mask:0xf
	s_nop 1
	v_add_f32_dpp v166, v166, v166 row_shr:4 row_mask:0xf bank_mask:0xf
	s_nop 1
	v_add_f32_dpp v166, v166, v166 row_shr:8 row_mask:0xf bank_mask:0xf
	s_nop 1
	v_add_f32_dpp v166, v166, v166 row_bcast:15 row_mask:0xa bank_mask:0xf
	s_nop 1
	v_add_f32_dpp v166, v166, v166 row_bcast:31 row_mask:0xc bank_mask:0xf
	s_nop 0
	v_readlane_b32 s26, v166, 63
	global_load_dwordx4 v[30:33], v[52:53], off
	v_lshl_add_u64 v[22:23], v[14:15], 0, v[0:1]
	v_xor_b32_e32 v20, 2, v187
	v_cmp_lt_i32_e32 vcc, v20, v17
	s_nop 1
	v_cndmask_b32_e32 v20, v187, v20, vcc
	v_lshlrev_b32_e32 v20, 2, v20
	v_xor_b32_e32 v20, 4, v187
	v_cmp_lt_i32_e32 vcc, v20, v17
	s_nop 1
	v_cndmask_b32_e32 v20, v187, v20, vcc
	v_lshlrev_b32_e32 v20, 2, v20
	v_xor_b32_e32 v20, 8, v187
	v_cmp_lt_i32_e32 vcc, v20, v17
	s_nop 1
	v_cndmask_b32_e32 v20, v187, v20, vcc
	v_lshlrev_b32_e32 v20, 2, v20
	v_xor_b32_e32 v20, 16, v187
	v_cmp_lt_i32_e32 vcc, v20, v17
	s_nop 1
	v_cndmask_b32_e32 v20, v187, v20, vcc
	v_lshlrev_b32_e32 v20, 2, v20
	v_xor_b32_e32 v20, 32, v187
	v_cmp_lt_i32_e32 vcc, v20, v17
	s_nop 1
	v_cndmask_b32_e32 v17, v187, v20, vcc
	v_lshlrev_b32_e32 v17, 2, v17
	s_nop 1
	v_mov_b32_e32 v16, s26
	v_fmamk_f32 v16, v16, 0x3a800000, v183
	v_cmp_gt_f32_e32 vcc, s2, v16
	v_mul_f32_e32 v17, 0x4b800000, v16
	s_nop 0
	v_cndmask_b32_e32 v16, v16, v17, vcc
	v_rsq_f32_e32 v16, v16
	s_nop 0
	v_mul_f32_e32 v17, 0x45800000, v16
	v_cndmask_b32_e32 v20, v16, v17, vcc
	v_lshl_add_u64 v[16:17], v[18:19], 0, v[0:1]
	global_load_dwordx4 v[34:37], v[16:17], off
	v_pk_mul_f32 v[28:29], v[28:29], v[20:21] op_sel_hi:[1,0]
	global_load_dwordx4 v[14:17], v[22:23], off
	v_pk_mul_f32 v[26:27], v[26:27], v[20:21] op_sel_hi:[1,0]
	s_waitcnt vmcnt(2)
	v_pk_mul_f32 v[28:29], v[32:33], v[28:29]
	v_pk_mul_f32 v[26:27], v[30:31], v[26:27]
	v_pk_mul_f32 v[12:13], v[12:13], v[20:21] op_sel_hi:[1,0]
	v_pk_mul_f32 v[10:11], v[10:11], v[20:21] op_sel_hi:[1,0]
	v_pk_mul_f32 v[8:9], v[8:9], v[20:21] op_sel_hi:[1,0]
	v_pk_mul_f32 v[6:7], v[6:7], v[20:21] op_sel_hi:[1,0]
	v_pk_mul_f32 v[4:5], v[4:5], v[20:21] op_sel_hi:[1,0]
	v_pk_mul_f32 v[2:3], v[2:3], v[20:21] op_sel_hi:[1,0]
	s_waitcnt vmcnt(1)
	v_pk_add_f32 v[30:31], v[36:37], 1.0 op_sel_hi:[1,0]
	v_pk_add_f32 v[32:33], v[34:35], 1.0 op_sel_hi:[1,0]
	s_waitcnt vmcnt(0)
	v_pk_fma_f32 v[16:17], v[30:31], v[28:29], v[16:17]
	v_pk_fma_f32 v[14:15], v[32:33], v[26:27], v[14:15]
	ds_write_b128 v24, v[14:17]
	s_waitcnt vmcnt(6)
	v_mov_b64_e32 v[14:15], v[116:117]
	v_mov_b64_e32 v[16:17], v[118:119]
	v_lshl_add_u64 v[26:27], v[18:19], 0, v[78:79]
	v_mov_b64_e32 v[26:27], v[120:121]
	v_mov_b64_e32 v[28:29], v[122:123]
	s_nop 0
	v_mov_b64_e32 v[30:31], v[124:125]
	v_mov_b64_e32 v[32:33], v[126:127]
	v_pk_mul_f32 v[10:11], v[14:15], v[10:11]
	v_pk_mul_f32 v[12:13], v[16:17], v[12:13]
	v_pk_add_f32 v[14:15], v[28:29], 1.0 op_sel_hi:[1,0]
	v_pk_add_f32 v[16:17], v[26:27], 1.0 op_sel_hi:[1,0]
	v_pk_fma_f32 v[12:13], v[14:15], v[12:13], v[32:33]
	v_pk_fma_f32 v[10:11], v[16:17], v[10:11], v[30:31]
	ds_write_b128 v24, v[10:13] offset:1024
	s_waitcnt vmcnt(3)
	v_mov_b64_e32 v[10:11], v[128:129]
	v_mov_b64_e32 v[12:13], v[130:131]
	v_lshl_add_u64 v[14:15], v[18:19], 0, v[80:81]
	v_mov_b64_e32 v[14:15], v[132:133]
	v_mov_b64_e32 v[16:17], v[134:135]
	s_nop 0
	v_mov_b64_e32 v[26:27], v[140:141]
	v_mov_b64_e32 v[28:29], v[142:143]
	v_pk_mul_f32 v[6:7], v[10:11], v[6:7]
	v_pk_mul_f32 v[8:9], v[12:13], v[8:9]
	v_pk_add_f32 v[10:11], v[16:17], 1.0 op_sel_hi:[1,0]
	v_pk_add_f32 v[12:13], v[14:15], 1.0 op_sel_hi:[1,0]
	v_pk_fma_f32 v[8:9], v[10:11], v[8:9], v[28:29]
	v_pk_fma_f32 v[6:7], v[12:13], v[6:7], v[26:27]
	ds_write_b128 v24, v[6:9] offset:2048
	s_waitcnt vmcnt(0)
	v_mov_b64_e32 v[14:15], v[144:145]
	v_mov_b64_e32 v[16:17], v[146:147]
	v_lshl_add_u64 v[6:7], v[18:19], 0, v[82:83]
	v_mov_b64_e32 v[6:7], v[148:149]
	v_mov_b64_e32 v[8:9], v[150:151]
	s_nop 0
	v_mov_b64_e32 v[10:11], v[158:159]
	v_mov_b64_e32 v[12:13], v[160:161]
	v_pk_mul_f32 v[2:3], v[14:15], v[2:3]
	v_pk_mul_f32 v[4:5], v[16:17], v[4:5]
	v_pk_add_f32 v[8:9], v[8:9], 1.0 op_sel_hi:[1,0]
	v_pk_add_f32 v[6:7], v[6:7], 1.0 op_sel_hi:[1,0]
	v_pk_fma_f32 v[4:5], v[4:5], v[8:9], v[12:13]
	v_pk_fma_f32 v[2:3], v[2:3], v[6:7], v[10:11]
	ds_write_b128 v24, v[2:5] offset:3072
